# mix0: dynamic tile scheduling (block takes its first tile statically, then grabs the next index from an atomic counter, prefetched one tile ahead and broadcast through LDS): attention tiles first, gml
# speedup vs baseline: 1.0087x; 1.0087x over previous
.LBB0_248:
	s_or_b64 exec, exec, s[0:1]
	s_cmpk_gt_i32 s2, 0xbff
	v_lshlrev_b32_e32 v156, 9, v131
	v_lshlrev_b32_e32 v159, 2, v134
	v_lshlrev_b32_e32 v158, 5, v131
	s_waitcnt lgkmcnt(0)
	s_barrier
	s_cbranch_scc1 .LBB0_261
	v_lshlrev_b32_e32 v4, 13, v135
	v_lshl_add_u32 v6, v134, 3, v138
	v_lshl_or_b32 v8, v134, 11, v4
	v_lshlrev_b32_e32 v10, 5, v138
	v_or3_b32 v77, v4, v137, v10
	v_lshl_or_b32 v102, v6, 2, v8
	v_add_u32_e32 v10, 0x60, v6
	v_add_u32_e32 v6, 0x70, v6
	v_and_b32_e32 v10, 0x7f, v10
	v_and_b32_e32 v6, 0x7f, v6
	v_lshl_or_b32 v103, v10, 2, v8
	v_lshl_or_b32 v104, v6, 2, v8
	v_add_u32_e32 v8, 8, v133
	v_and_b32_e32 v8, 0x78, v8
	v_lshlrev_b32_e32 v6, 9, v136
	v_lshlrev_b32_e32 v8, 2, v8
	v_or3_b32 v106, v4, v6, v8
	v_add_u32_e32 v8, 16, v133
	v_and_b32_e32 v8, 0x78, v8
	v_lshlrev_b32_e32 v6, 9, v132
	v_lshlrev_b32_e32 v8, 2, v8
	v_or3_b32 v108, v4, v6, v8
	v_add_u32_e32 v8, 24, v133
	v_xor_b32_e32 v0, v128, v131
	v_and_b32_e32 v8, 0x78, v8
	v_lshlrev_b32_e32 v1, 3, v0
	v_lshlrev_b32_e32 v6, 9, v130
	v_lshlrev_b32_e32 v8, 2, v8
	v_and_b32_e32 v0, 56, v1
	s_movk_i32 s0, 0x1e0
	v_or3_b32 v110, v4, v6, v8
	v_and_b32_e32 v6, 0x78, v1
	v_xor_b32_e32 v1, 1, v134
	v_and_or_b32 v2, v153, s0, v138
	v_cmp_gt_u32_e64 s[0:1], v1, v134
	v_xor_b32_e32 v1, 2, v134
	v_cmp_gt_u32_e64 s[22:23], v1, v134
	v_xor_b32_e32 v1, 3, v134
	v_cmp_gt_u32_e64 s[4:5], v1, v134
	v_bitop3_b32 v1, v134, v131, 15 bitop3:0x78
	v_lshlrev_b32_e32 v120, 4, v1
	v_bitop3_b32 v1, v134, v138, 4 bitop3:0x36
	v_lshlrev_b32_e32 v121, 4, v1
	v_bitop3_b32 v1, v134, v138, 8 bitop3:0x36
	v_lshlrev_b32_e32 v122, 4, v1
	v_bitop3_b32 v1, v134, v138, 12 bitop3:0x36
	v_lshlrev_b32_e32 v123, 4, v1
	v_xor_b32_e32 v1, v134, v131
	v_lshlrev_b32_e32 v1, 3, v1
	v_and_b32_e32 v124, 0x70, v1
	v_bitop3_b32 v1, v134, v131, 4 bitop3:0x36
	v_lshlrev_b32_e32 v1, 3, v1
	v_and_b32_e32 v125, 0x70, v1
	v_bitop3_b32 v1, v134, v131, 8 bitop3:0x36
	v_lshlrev_b32_e32 v1, 3, v1
	v_and_b32_e32 v126, 0x70, v1
	v_bitop3_b32 v1, v134, v131, 12 bitop3:0x36
	v_mov_b32_e32 v72, 0
	v_lshlrev_b32_e32 v1, 3, v1
	v_and_b32_e32 v127, 0x70, v1
	v_mul_u32_u24_e32 v1, 0x210, v138
	s_movk_i32 s8, 0x2100
	v_and_b32_e32 v10, 0x7f00, v158
	v_mov_b32_e32 v11, v72
	v_mad_u32_u24 v1, v135, s8, v1
	s_movk_i32 s8, 0xfe10
	v_lshl_add_u64 v[12:13], s[50:51], 0, v[10:11]
	v_lshlrev_b32_e32 v14, 1, v0
	v_mov_b32_e32 v15, v72
	s_add_u32 s30, s50, 0x9a00000
	v_lshlrev_b32_e32 v9, 5, v135
	v_mad_i32_i24 v16, v138, s8, v1
	v_lshl_add_u64 v[12:13], v[12:13], 0, v[14:15]
	s_mov_b64 s[8:9], 0x1080000
	v_lshl_add_u64 v[10:11], s[48:49], 0, v[10:11]
	s_addc_u32 s31, s51, 0
	v_bitop3_b32 v3, v128, v139, 3 bitop3:0x6c
	v_or_b32_e32 v4, 16, v9
	v_lshl_add_u64 v[78:79], v[12:13], 0, s[8:9]
	v_lshl_add_u64 v[10:11], v[10:11], 0, v[14:15]
	s_mov_b64 s[8:9], 0x2000000
	s_add_u32 s34, s50, 0xba00000
	v_lshlrev_b32_e32 v75, 7, v138
	v_lshlrev_b32_e32 v3, 4, v3
	v_lshlrev_b32_e32 v5, 7, v2
	v_lshlrev_b32_e32 v7, 4, v152
	v_lshlrev_b32_e32 v2, 3, v138
	v_or_b32_e32 v105, v134, v9
	v_or_b32_e32 v107, v136, v9
	v_or_b32_e32 v109, v132, v9
	v_or_b32_e32 v111, v130, v9
	v_or_b32_e32 v74, v4, v134
	v_or_b32_e32 v112, v136, v4
	v_or_b32_e32 v113, v132, v4
	v_or_b32_e32 v114, v130, v4
	v_lshlrev_b32_e32 v76, 4, v135
	v_lshlrev_b32_e32 v4, 3, v134
	v_and_b32_e32 v8, 0x7f000, v156
	v_mov_b32_e32 v118, 0x10000
	v_and_b32_e32 v9, 48, v131
	v_mul_u32_u24_e32 v17, 0x210, v134
	v_lshl_add_u64 v[80:81], v[10:11], 0, s[8:9]
	s_addc_u32 s35, s51, 0
	v_lshlrev_b32_e32 v10, 1, v6
	v_mov_b32_e32 v11, v72
	v_or_b32_e32 v115, v76, v138
	v_lshlrev_b32_e32 v116, 8, v138
	v_and_b32_e32 v117, 8, v4
	s_mov_b32 s29, 0
	v_cmp_eq_u32_e64 s[6:7], 0, v141
	v_lshl_or_b32 v119, v135, 2, v118
	v_lshl_add_u64 v[82:83], s[34:35], 0, v[10:11]
	s_xor_b32 s33, s2, 63
	s_mov_b64 s[38:39], 0x2000
	v_add_u32_e32 v141, 0x1000, v129
	s_mov_b64 s[46:47], 0x4000
	v_add_u32_e32 v142, 0x2000, v129
	s_mov_b64 s[52:53], 0x6000
	v_add_u32_e32 v143, 0x3000, v129
	v_or_b32_e32 v144, 0x4000, v129
	v_add_u32_e32 v145, 0x5000, v129
	v_add_u32_e32 v146, 0x6000, v129
	v_add_u32_e32 v147, 0x7000, v129
	s_mov_b64 s[56:57], 0x80
	v_or_b32_e32 v148, 0x8000, v129
	s_mov_b64 s[58:59], 0x2080
	v_add_u32_e32 v150, 0x9000, v129
	s_mov_b64 s[60:61], 0x4080
	v_add_u32_e32 v151, 0xa000, v129
	s_mov_b64 s[64:65], 0x6080
	v_add_u32_e32 v160, 0xb000, v129
	v_or_b32_e32 v161, 0xc000, v129
	v_add_u32_e32 v162, 0xd000, v129
	v_add_u32_e32 v163, 0xe000, v129
	v_add_u32_e32 v164, 0xf000, v129
	v_add_u32_e32 v165, v3, v5
	v_add_u32_e32 v166, v3, v75
	v_add_u32_e32 v167, v7, v5
	v_add_u32_e32 v168, v7, v75
	s_movk_i32 s84, 0x7fff
	s_mov_b32 s85, 0x7060302
	v_lshlrev_b32_e32 v84, 1, v4
	v_lshlrev_b32_e32 v86, 1, v6
	s_mov_b64 s[66:67], 0x8000
	s_mov_b64 s[70:71], 0x10000
	s_mov_b64 s[72:73], 0x18000
	v_lshlrev_b32_e32 v88, 1, v8
	v_lshlrev_b32_e32 v90, 1, v0
	s_mov_b64 s[74:75], 0x40000
	s_mov_b64 s[76:77], 0x80000
	s_mov_b64 s[78:79], 0xc0000
	s_mov_b32 s86, 0xc3200000
	v_add_u32_e32 v169, v1, v9
	v_add_u32_e32 v170, v16, v17
	s_mov_b32 s87, 0x5a00000
	v_add_u32_e32 v171, 0x400, v102
	v_lshlrev_b32_e32 v92, 1, v2
	v_mbcnt_hi_u32_b32 v172, -1, v155
	s_mov_b32 s88, s2
	v_readfirstlane_b32 s99, v129
	s_branch .LBB0_252

.LBB0_251:
	s_cmp_lg_u32 s99, 0
	s_cbranch_scc1 .Lmy_m0_rd
	s_add_i32 s101, s101, s3
	v_mov_b32_e32 v100, s101
	v_mov_b32_e32 v101, 0x10018
	ds_write_b32 v101, v100
	s_waitcnt lgkmcnt(0)
.Lmy_m0_rd:
	s_barrier
	v_mov_b32_e32 v101, 0x10018
	ds_read_b32 v100, v101
	s_waitcnt lgkmcnt(0)
	v_readfirstlane_b32 s88, v100
	s_xor_b32 s33, s88, 63
	s_cmpk_lt_i32 s88, 0xc00
	s_cbranch_scc0 .LBB0_261
.LBB0_252:
	s_cmp_lg_u32 s99, 0
	s_cbranch_scc1 .Lmy_m0_noat
	s_mov_b64 s[94:95], exec
	s_mov_b64 exec, 1
	v_mov_b32_e32 v101, 0x3840
	v_mov_b32_e32 v100, 1
	global_atomic_add v100, v101, v100, s[96:97] sc0
	s_mov_b64 exec, s[94:95]

.LBB0_254:
	s_and_b32 s20, s88, 7
	s_add_i32 s24, s88, 0xfffff800
	s_lshr_b32 s25, s24, 3
	s_lshl_b32 s32, s20, 15
	s_add_u32 s8, s50, s32
	s_addc_u32 s9, s51, 0
	s_add_u32 s8, s8, 0x1080000
	s_addc_u32 s9, s9, 0
	s_lshl_b32 s32, s24, 15
	s_add_u32 s10, s48, s32
	s_addc_u32 s11, s49, 0
	s_add_u32 s10, s10, 0x2000000
	s_addc_u32 s11, s11, 0
	s_lshl_b32 s20, s20, 8
	s_lshl_b32 s32, s25, 19
	s_add_i32 s32, s32, s20
	s_add_u32 s12, s50, s32
	s_addc_u32 s13, s51, 0
	s_add_u32 s12, s12, 0x5a00000
	s_addc_u32 s13, s13, 0
	s_mov_b32 s82, s12
	s_mov_b32 s83, s13
	s_lshl_b32 s32, s25, 18
	s_add_i32 s32, s32, s20
	s_add_u32 s14, s48, s32
	s_addc_u32 s15, s49, 0
	s_lshl_b32 s32, s20, 1
	s_add_u32 s80, s54, s32
	s_addc_u32 s81, s55, 0
	v_lshrrev_b32_e32 v73, 4, v129
	v_and_b32_e32 v0, 15, v73
	v_bfe_u32 v1, v73, 4, 2
	v_bfe_u32 v2, v73, 1, 3
	v_xor_b32_e32 v2, v1, v2
	v_lshlrev_b32_e32 v2, 4, v2
	v_lshl_or_b32 v89, v0, 7, v2
	v_xor_b32_e32 v91, 64, v89
	v_lshrrev_b32_e32 v2, 6, v73
	v_lshl_add_u32 v85, v2, 12, v89
	v_lshl_add_u32 v87, v2, 12, v91
	v_bfe_u32 v3, v73, 4, 3
	v_and_b32_e32 v4, 7, v73
	v_xor_b32_e32 v3, v3, v4
	v_lshlrev_b32_e32 v3, 4, v3
	v_lshrrev_b32_e32 v4, 3, v73
	v_lshl_or_b32 v93, v4, 8, v3
	v_add_u32_e32 v173, 8192, v93
	v_add_u32_e32 v234, 16384, v93
	v_add_u32_e32 v235, 24576, v93
	v_lshl_add_u32 v5, v2, 5, v1
	v_lshlrev_b32_e32 v6, 4, v0
	v_lshl_add_u32 v236, v5, 12, v6
	v_lshl_add_u32 v237, v5, 11, v6
	v_lshlrev_b32_e32 v238, 2, v5
	v_lshlrev_b32_e32 v5, 13, v2
	v_lshl_add_u32 v6, v1, 3, v0
	v_lshl_add_u32 v7, v1, 11, v5
	v_lshl_add_u32 v239, v6, 2, v7
	v_add_u32_e32 v8, 0x60, v6
	v_and_b32_e32 v8, 0x7f, v8
	v_lshl_add_u32 v240, v8, 2, v7
	v_add_u32_e32 v8, 0x70, v6
	v_and_b32_e32 v8, 0x7f, v8
	v_lshl_add_u32 v241, v8, 2, v7
	v_lshlrev_b32_e32 v8, 3, v0
	v_lshl_add_u32 v10, v1, 9, v5
	v_add_u32_e32 v9, 0, v8
	v_and_b32_e32 v9, 0x7f, v9
	v_lshl_add_u32 v242, v9, 2, v10
	v_add_u32_e32 v9, 8, v8
	v_and_b32_e32 v9, 0x7f, v9
	v_lshl_add_u32 v243, v9, 2, v10
	v_add_u32_e32 v243, 2048, v243
	v_add_u32_e32 v9, 16, v8
	v_and_b32_e32 v9, 0x7f, v9
	v_lshl_add_u32 v244, v9, 2, v10
	v_add_u32_e32 v244, 4096, v244
	v_add_u32_e32 v9, 24, v8
	v_and_b32_e32 v9, 0x7f, v9
	v_lshl_add_u32 v245, v9, 2, v10
	v_add_u32_e32 v245, 6144, v245
	v_readfirstlane_b32 s89, v129
	s_barrier
	s_add_u32 m0, s89, 0
	v_mov_b32_e32 v0, 0
	v_mov_b32_e32 v1, 0
	global_load_lds_dwordx4 v93, s[8:9]
	s_add_u32 m0, s89, 4096
	v_mov_b32_e32 v2, 0
	v_mov_b32_e32 v3, 0
	global_load_lds_dwordx4 v173, s[8:9]
	s_add_u32 m0, s89, 8192
	v_mov_b32_e32 v4, 0
	v_mov_b32_e32 v5, 0
	global_load_lds_dwordx4 v234, s[8:9]
	s_add_u32 m0, s89, 12288
	v_mov_b32_e32 v6, 0
	v_mov_b32_e32 v7, 0
	global_load_lds_dwordx4 v235, s[8:9]
	s_add_u32 s8, s8, 128
	s_addc_u32 s9, s9, 0
	s_add_u32 m0, s89, 16384
	v_mov_b32_e32 v8, 0
	v_mov_b32_e32 v9, 0
	global_load_lds_dwordx4 v93, s[10:11]
	s_add_u32 m0, s89, 20480
	v_mov_b32_e32 v10, 0
	v_mov_b32_e32 v11, 0
	global_load_lds_dwordx4 v173, s[10:11]
	s_add_u32 m0, s89, 24576
	v_mov_b32_e32 v12, 0
	v_mov_b32_e32 v13, 0
	global_load_lds_dwordx4 v234, s[10:11]
	s_add_u32 m0, s89, 28672
	v_mov_b32_e32 v14, 0
	v_mov_b32_e32 v15, 0
	global_load_lds_dwordx4 v235, s[10:11]
	s_add_u32 s10, s10, 128
	s_addc_u32 s11, s11, 0
	s_add_u32 m0, s89, 32768
	v_mov_b32_e32 v16, 0
	v_mov_b32_e32 v17, 0
	global_load_lds_dwordx4 v93, s[8:9]
	s_add_u32 m0, s89, 36864
	v_mov_b32_e32 v18, 0
	v_mov_b32_e32 v19, 0
	global_load_lds_dwordx4 v173, s[8:9]
	s_add_u32 m0, s89, 40960
	v_mov_b32_e32 v20, 0
	v_mov_b32_e32 v21, 0
	global_load_lds_dwordx4 v234, s[8:9]
	s_add_u32 m0, s89, 45056
	v_mov_b32_e32 v22, 0
	v_mov_b32_e32 v23, 0
	global_load_lds_dwordx4 v235, s[8:9]
	s_add_u32 m0, s89, 49152
	v_mov_b32_e32 v24, 0
	v_mov_b32_e32 v25, 0
	global_load_lds_dwordx4 v93, s[10:11]
	s_add_u32 m0, s89, 53248
	v_mov_b32_e32 v26, 0
	v_mov_b32_e32 v27, 0
	global_load_lds_dwordx4 v173, s[10:11]
	s_add_u32 m0, s89, 57344
	v_mov_b32_e32 v28, 0
	v_mov_b32_e32 v29, 0
	global_load_lds_dwordx4 v234, s[10:11]
	s_add_u32 m0, s89, 61440
	v_mov_b32_e32 v30, 0
	v_mov_b32_e32 v31, 0
	global_load_lds_dwordx4 v235, s[10:11]
	global_load_dwordx4 v[198:201], v236, s[12:13]
	global_load_dwordx4 v[214:217], v237, s[14:15]
	global_load_dword v230, v238, s[80:81] offset:0
	s_add_u32 s12, s12, 0x4000
	s_addc_u32 s13, s13, 0
	s_add_u32 s14, s14, 0x2000
	s_addc_u32 s15, s15, 0
	global_load_dwordx4 v[202:205], v236, s[12:13]
	global_load_dwordx4 v[218:221], v237, s[14:15]
	global_load_dword v231, v238, s[80:81] offset:16
	s_add_u32 s12, s12, 0x4000
	s_addc_u32 s13, s13, 0
	s_add_u32 s14, s14, 0x2000
	s_addc_u32 s15, s15, 0
	global_load_dwordx4 v[206:209], v236, s[12:13]
	global_load_dwordx4 v[222:225], v237, s[14:15]
	global_load_dword v232, v238, s[80:81] offset:32
	s_add_u32 s12, s12, 0x4000
	s_addc_u32 s13, s13, 0
	s_add_u32 s14, s14, 0x2000
	s_addc_u32 s15, s15, 0
	global_load_dwordx4 v[210:213], v236, s[12:13]
	global_load_dwordx4 v[226:229], v237, s[14:15]
	global_load_dword v233, v238, s[80:81] offset:48
	s_add_u32 s12, s12, 0x4000
	s_addc_u32 s13, s13, 0
	s_add_u32 s14, s14, 0x2000
	s_addc_u32 s15, s15, 0
	v_mov_b32_e32 v32, 0
	v_mov_b32_e32 v33, 0
	v_mov_b32_e32 v34, 0
	v_mov_b32_e32 v35, 0
	v_mov_b32_e32 v36, 0
	v_mov_b32_e32 v37, 0
	v_mov_b32_e32 v38, 0
	v_mov_b32_e32 v39, 0
	v_mov_b32_e32 v40, 0
	v_mov_b32_e32 v41, 0
	v_mov_b32_e32 v42, 0
	v_mov_b32_e32 v43, 0
	v_mov_b32_e32 v44, 0
	v_mov_b32_e32 v45, 0
	v_mov_b32_e32 v46, 0
	v_mov_b32_e32 v47, 0
	v_mov_b32_e32 v48, 0
	v_mov_b32_e32 v49, 0
	v_mov_b32_e32 v50, 0
	v_mov_b32_e32 v51, 0
	v_mov_b32_e32 v52, 0
	v_mov_b32_e32 v53, 0
	v_mov_b32_e32 v54, 0
	v_mov_b32_e32 v55, 0
	v_mov_b32_e32 v56, 0
	v_mov_b32_e32 v57, 0
	v_mov_b32_e32 v58, 0
	v_mov_b32_e32 v59, 0
	v_mov_b32_e32 v60, 0
	v_mov_b32_e32 v61, 0
	v_mov_b32_e32 v62, 0
	v_mov_b32_e32 v63, 0
	s_waitcnt vmcnt(12)
	v_readfirstlane_b32 s101, v100
	s_barrier
	ds_read_b128 v[64:67], v85 offset:0
	ds_read_b128 v[68:71], v85 offset:2048
	ds_read_b128 v[174:177], v89 offset:16384
	ds_read_b128 v[178:181], v89 offset:18432
	ds_read_b128 v[182:185], v89 offset:20480
	ds_read_b128 v[186:189], v89 offset:22528
	ds_read_b128 v[190:193], v89 offset:24576
	ds_read_b128 v[194:197], v89 offset:26624
	s_waitcnt lgkmcnt(5)
	v_mfma_f32_16x16x32_bf16 v[0:3], v[64:67], v[174:177], v[0:3]
	v_mfma_f32_16x16x32_bf16 v[32:35], v[68:71], v[174:177], v[32:35]
	ds_read_b128 v[174:177], v89 offset:28672
	s_waitcnt lgkmcnt(5)
	v_mfma_f32_16x16x32_bf16 v[4:7], v[64:67], v[178:181], v[4:7]
	v_mfma_f32_16x16x32_bf16 v[36:39], v[68:71], v[178:181], v[36:39]
	ds_read_b128 v[178:181], v89 offset:30720
	s_waitcnt lgkmcnt(5)
	v_mfma_f32_16x16x32_bf16 v[8:11], v[64:67], v[182:185], v[8:11]
	v_mfma_f32_16x16x32_bf16 v[40:43], v[68:71], v[182:185], v[40:43]
	ds_read_b128 v[94:97], v87 offset:0
	ds_read_b128 v[98:101], v87 offset:2048
	ds_read_b128 v[182:185], v91 offset:16384
	s_waitcnt lgkmcnt(7)
	v_mfma_f32_16x16x32_bf16 v[12:15], v[64:67], v[186:189], v[12:15]
	v_mfma_f32_16x16x32_bf16 v[44:47], v[68:71], v[186:189], v[44:47]
	ds_read_b128 v[186:189], v91 offset:18432
	s_waitcnt lgkmcnt(7)
	v_mfma_f32_16x16x32_bf16 v[16:19], v[64:67], v[190:193], v[16:19]
	v_mfma_f32_16x16x32_bf16 v[48:51], v[68:71], v[190:193], v[48:51]
	ds_read_b128 v[190:193], v91 offset:20480
	s_waitcnt lgkmcnt(7)
	v_mfma_f32_16x16x32_bf16 v[20:23], v[64:67], v[194:197], v[20:23]
	v_mfma_f32_16x16x32_bf16 v[52:55], v[68:71], v[194:197], v[52:55]
	ds_read_b128 v[194:197], v91 offset:22528
	s_waitcnt lgkmcnt(7)
	v_mfma_f32_16x16x32_bf16 v[24:27], v[64:67], v[174:177], v[24:27]
	v_mfma_f32_16x16x32_bf16 v[56:59], v[68:71], v[174:177], v[56:59]
	ds_read_b128 v[174:177], v91 offset:24576
	s_waitcnt lgkmcnt(7)
	v_mfma_f32_16x16x32_bf16 v[28:31], v[64:67], v[178:181], v[28:31]
	v_mfma_f32_16x16x32_bf16 v[60:63], v[68:71], v[178:181], v[60:63]
	ds_read_b128 v[178:181], v91 offset:26624
	s_waitcnt lgkmcnt(5)
	v_mfma_f32_16x16x32_bf16 v[0:3], v[94:97], v[182:185], v[0:3]
	v_mfma_f32_16x16x32_bf16 v[32:35], v[98:101], v[182:185], v[32:35]
	ds_read_b128 v[182:185], v91 offset:28672
	s_waitcnt lgkmcnt(5)
	v_mfma_f32_16x16x32_bf16 v[4:7], v[94:97], v[186:189], v[4:7]
	v_mfma_f32_16x16x32_bf16 v[36:39], v[98:101], v[186:189], v[36:39]
	ds_read_b128 v[186:189], v91 offset:30720
	s_waitcnt lgkmcnt(5)
	v_mfma_f32_16x16x32_bf16 v[8:11], v[94:97], v[190:193], v[8:11]
	v_mfma_f32_16x16x32_bf16 v[40:43], v[98:101], v[190:193], v[40:43]
	ds_read_b128 v[64:67], v85 offset:32768
	ds_read_b128 v[68:71], v85 offset:34816
	ds_read_b128 v[190:193], v89 offset:49152
	s_waitcnt lgkmcnt(7)
	v_mfma_f32_16x16x32_bf16 v[12:15], v[94:97], v[194:197], v[12:15]
	v_mfma_f32_16x16x32_bf16 v[44:47], v[98:101], v[194:197], v[44:47]
	ds_read_b128 v[194:197], v89 offset:51200
	s_waitcnt lgkmcnt(7)
	v_mfma_f32_16x16x32_bf16 v[16:19], v[94:97], v[174:177], v[16:19]
	v_mfma_f32_16x16x32_bf16 v[48:51], v[98:101], v[174:177], v[48:51]
	ds_read_b128 v[174:177], v89 offset:53248
	s_waitcnt lgkmcnt(7)
	v_mfma_f32_16x16x32_bf16 v[20:23], v[94:97], v[178:181], v[20:23]
	v_mfma_f32_16x16x32_bf16 v[52:55], v[98:101], v[178:181], v[52:55]
	ds_read_b128 v[178:181], v89 offset:55296
	s_waitcnt lgkmcnt(7)
	v_mfma_f32_16x16x32_bf16 v[24:27], v[94:97], v[182:185], v[24:27]
	v_mfma_f32_16x16x32_bf16 v[56:59], v[98:101], v[182:185], v[56:59]
	ds_read_b128 v[182:185], v89 offset:57344
	s_waitcnt lgkmcnt(7)
	v_mfma_f32_16x16x32_bf16 v[28:31], v[94:97], v[186:189], v[28:31]
	v_mfma_f32_16x16x32_bf16 v[60:63], v[98:101], v[186:189], v[60:63]
	ds_read_b128 v[186:189], v89 offset:59392
	s_waitcnt lgkmcnt(5)
	v_mfma_f32_16x16x32_bf16 v[0:3], v[64:67], v[190:193], v[0:3]
	v_mfma_f32_16x16x32_bf16 v[32:35], v[68:71], v[190:193], v[32:35]
	ds_read_b128 v[190:193], v89 offset:61440
	s_waitcnt lgkmcnt(5)
	v_mfma_f32_16x16x32_bf16 v[4:7], v[64:67], v[194:197], v[4:7]
	v_mfma_f32_16x16x32_bf16 v[36:39], v[68:71], v[194:197], v[36:39]
	ds_read_b128 v[194:197], v89 offset:63488
	s_waitcnt lgkmcnt(5)
	v_mfma_f32_16x16x32_bf16 v[8:11], v[64:67], v[174:177], v[8:11]
	v_mfma_f32_16x16x32_bf16 v[40:43], v[68:71], v[174:177], v[40:43]
	ds_read_b128 v[94:97], v87 offset:32768
	ds_read_b128 v[98:101], v87 offset:34816
	ds_read_b128 v[174:177], v91 offset:49152
	s_waitcnt lgkmcnt(7)
	v_mfma_f32_16x16x32_bf16 v[12:15], v[64:67], v[178:181], v[12:15]
	v_mfma_f32_16x16x32_bf16 v[44:47], v[68:71], v[178:181], v[44:47]
	ds_read_b128 v[178:181], v91 offset:51200
	s_waitcnt lgkmcnt(7)
	v_mfma_f32_16x16x32_bf16 v[16:19], v[64:67], v[182:185], v[16:19]
	v_mfma_f32_16x16x32_bf16 v[48:51], v[68:71], v[182:185], v[48:51]
	ds_read_b128 v[182:185], v91 offset:53248
	s_waitcnt lgkmcnt(7)
	v_mfma_f32_16x16x32_bf16 v[20:23], v[64:67], v[186:189], v[20:23]
	v_mfma_f32_16x16x32_bf16 v[52:55], v[68:71], v[186:189], v[52:55]
	ds_read_b128 v[186:189], v91 offset:55296
	s_waitcnt lgkmcnt(7)
	v_mfma_f32_16x16x32_bf16 v[24:27], v[64:67], v[190:193], v[24:27]
	v_mfma_f32_16x16x32_bf16 v[56:59], v[68:71], v[190:193], v[56:59]
	ds_read_b128 v[190:193], v91 offset:57344
	s_waitcnt lgkmcnt(7)
	v_mfma_f32_16x16x32_bf16 v[28:31], v[64:67], v[194:197], v[28:31]
	v_mfma_f32_16x16x32_bf16 v[60:63], v[68:71], v[194:197], v[60:63]
	ds_read_b128 v[194:197], v91 offset:59392
	s_waitcnt lgkmcnt(5)
	v_mfma_f32_16x16x32_bf16 v[0:3], v[94:97], v[174:177], v[0:3]
	v_mfma_f32_16x16x32_bf16 v[32:35], v[98:101], v[174:177], v[32:35]
	ds_read_b128 v[174:177], v91 offset:61440
	s_waitcnt lgkmcnt(5)
	v_mfma_f32_16x16x32_bf16 v[4:7], v[94:97], v[178:181], v[4:7]
	v_mfma_f32_16x16x32_bf16 v[36:39], v[98:101], v[178:181], v[36:39]
	ds_read_b128 v[178:181], v91 offset:63488
	s_waitcnt lgkmcnt(5)
	v_mfma_f32_16x16x32_bf16 v[8:11], v[94:97], v[182:185], v[8:11]
	v_mfma_f32_16x16x32_bf16 v[40:43], v[98:101], v[182:185], v[40:43]
	s_waitcnt lgkmcnt(4)
	v_mfma_f32_16x16x32_bf16 v[12:15], v[94:97], v[186:189], v[12:15]
	v_mfma_f32_16x16x32_bf16 v[44:47], v[98:101], v[186:189], v[44:47]
	s_waitcnt lgkmcnt(3)
	v_mfma_f32_16x16x32_bf16 v[16:19], v[94:97], v[190:193], v[16:19]
	v_mfma_f32_16x16x32_bf16 v[48:51], v[98:101], v[190:193], v[48:51]
	s_waitcnt lgkmcnt(2)
	v_mfma_f32_16x16x32_bf16 v[20:23], v[94:97], v[194:197], v[20:23]
	v_mfma_f32_16x16x32_bf16 v[52:55], v[98:101], v[194:197], v[52:55]
	s_waitcnt lgkmcnt(1)
	v_mfma_f32_16x16x32_bf16 v[24:27], v[94:97], v[174:177], v[24:27]
	v_mfma_f32_16x16x32_bf16 v[56:59], v[98:101], v[174:177], v[56:59]
	s_waitcnt lgkmcnt(0)
	v_mfma_f32_16x16x32_bf16 v[28:31], v[94:97], v[178:181], v[28:31]
	v_mfma_f32_16x16x32_bf16 v[60:63], v[98:101], v[178:181], v[60:63]
	global_load_dwordx4 v[174:177], v236, s[12:13]
	global_load_dwordx4 v[190:193], v237, s[14:15]
	global_load_dword v94, v238, s[80:81] offset:64
	s_add_u32 s12, s12, 0x4000
	s_addc_u32 s13, s13, 0
	s_add_u32 s14, s14, 0x2000
	s_addc_u32 s15, s15, 0
	global_load_dwordx4 v[178:181], v236, s[12:13]
	global_load_dwordx4 v[194:197], v237, s[14:15]
	global_load_dword v95, v238, s[80:81] offset:80
	s_add_u32 s12, s12, 0x4000
	s_addc_u32 s13, s13, 0
	s_add_u32 s14, s14, 0x2000
	s_addc_u32 s15, s15, 0
	global_load_dwordx4 v[182:185], v236, s[12:13]
	global_load_dwordx4 v[64:67], v237, s[14:15]
	global_load_dword v96, v238, s[80:81] offset:96
	s_add_u32 s12, s12, 0x4000
	s_addc_u32 s13, s13, 0
	s_add_u32 s14, s14, 0x2000
	s_addc_u32 s15, s15, 0
	global_load_dwordx4 v[186:189], v236, s[12:13]
	global_load_dwordx4 v[68:71], v237, s[14:15]
	global_load_dword v97, v238, s[80:81] offset:112
	s_add_u32 s12, s12, 0x4000
	s_addc_u32 s13, s13, 0
	s_add_u32 s14, s14, 0x2000
	s_addc_u32 s15, s15, 0
	s_nop 7
	s_waitcnt lgkmcnt(0)
	s_barrier
	ds_write_b32 v239, v0 offset:0
	ds_write_b32 v239, v1 offset:512
	ds_write_b32 v239, v2 offset:1024
	ds_write_b32 v239, v3 offset:1536
	ds_write_b32 v239, v4 offset:64
	ds_write_b32 v239, v5 offset:576
	ds_write_b32 v239, v6 offset:1088
	ds_write_b32 v239, v7 offset:1600
	ds_write_b32 v239, v8 offset:128
	ds_write_b32 v239, v9 offset:640
	ds_write_b32 v239, v10 offset:1152
	ds_write_b32 v239, v11 offset:1664
	ds_write_b32 v239, v12 offset:192
	ds_write_b32 v239, v13 offset:704
	ds_write_b32 v239, v14 offset:1216
	ds_write_b32 v239, v15 offset:1728
	ds_write_b32 v239, v16 offset:256
	ds_write_b32 v239, v17 offset:768
	ds_write_b32 v239, v18 offset:1280
	ds_write_b32 v239, v19 offset:1792
	ds_write_b32 v239, v20 offset:320
	ds_write_b32 v239, v21 offset:832
	ds_write_b32 v239, v22 offset:1344
	ds_write_b32 v239, v23 offset:1856
	ds_write_b32 v240, v24 offset:0
	ds_write_b32 v240, v25 offset:512
	ds_write_b32 v240, v26 offset:1024
	ds_write_b32 v240, v27 offset:1536
	ds_write_b32 v241, v28 offset:0
	ds_write_b32 v241, v29 offset:512
	ds_write_b32 v241, v30 offset:1024
	ds_write_b32 v241, v31 offset:1536
	s_waitcnt lgkmcnt(0)
	ds_read_b128 v[0:3], v242
	ds_read_b128 v[4:7], v242 offset:16
	ds_read_b128 v[8:11], v243
	ds_read_b128 v[12:15], v243 offset:16
	ds_read_b128 v[16:19], v244
	ds_read_b128 v[20:23], v244 offset:16
	ds_read_b128 v[24:27], v245
	ds_read_b128 v[28:31], v245 offset:16
	s_waitcnt vmcnt(21) lgkmcnt(6)
	v_add_f32_e32 v0, v0, v230
	v_add_f32_e32 v1, v1, v230
	v_add_f32_e32 v2, v2, v230
	v_add_f32_e32 v3, v3, v230
	v_add_f32_e32 v4, v4, v230
	v_add_f32_e32 v5, v5, v230
	v_add_f32_e32 v6, v6, v230
	v_add_f32_e32 v7, v7, v230
	v_lshlrev_b32_e32 v98, 16, v214
	v_lshlrev_b32_e32 v99, 16, v215
	v_lshlrev_b32_e32 v100, 16, v216
	v_lshlrev_b32_e32 v101, 16, v217
	v_and_b32_e32 v214, 0xffff0000, v214
	v_and_b32_e32 v215, 0xffff0000, v215
	v_and_b32_e32 v216, 0xffff0000, v216
	v_and_b32_e32 v217, 0xffff0000, v217
	v_mul_f32_e32 v0, v0, v98
	v_mul_f32_e32 v1, v1, v214
	v_mul_f32_e32 v2, v2, v99
	v_mul_f32_e32 v3, v3, v215
	v_mul_f32_e32 v4, v4, v100
	v_mul_f32_e32 v5, v5, v216
	v_mul_f32_e32 v6, v6, v101
	v_mul_f32_e32 v7, v7, v217
	v_lshlrev_b32_e32 v98, 16, v198
	v_lshlrev_b32_e32 v99, 16, v199
	v_lshlrev_b32_e32 v100, 16, v200
	v_lshlrev_b32_e32 v101, 16, v201
	v_and_b32_e32 v198, 0xffff0000, v198
	v_and_b32_e32 v199, 0xffff0000, v199
	v_and_b32_e32 v200, 0xffff0000, v200
	v_and_b32_e32 v201, 0xffff0000, v201
	v_mul_f32_e32 v0, v0, v98
	v_mul_f32_e32 v1, v1, v198
	v_mul_f32_e32 v2, v2, v99
	v_mul_f32_e32 v3, v3, v199
	v_mul_f32_e32 v4, v4, v100
	v_mul_f32_e32 v5, v5, v200
	v_mul_f32_e32 v6, v6, v101
	v_mul_f32_e32 v7, v7, v201
	v_cvt_pk_bf16_f32 v0, v0, v1
	v_cvt_pk_bf16_f32 v1, v2, v3
	v_cvt_pk_bf16_f32 v2, v4, v5
	v_cvt_pk_bf16_f32 v3, v6, v7
	global_store_dwordx4 v236, v[0:3], s[82:83]
	s_add_u32 s82, s82, 0x4000
	s_addc_u32 s83, s83, 0
	s_waitcnt vmcnt(19) lgkmcnt(4)
	v_add_f32_e32 v8, v8, v231
	v_add_f32_e32 v9, v9, v231
	v_add_f32_e32 v10, v10, v231
	v_add_f32_e32 v11, v11, v231
	v_add_f32_e32 v12, v12, v231
	v_add_f32_e32 v13, v13, v231
	v_add_f32_e32 v14, v14, v231
	v_add_f32_e32 v15, v15, v231
	v_lshlrev_b32_e32 v98, 16, v218
	v_lshlrev_b32_e32 v99, 16, v219
	v_lshlrev_b32_e32 v100, 16, v220
	v_lshlrev_b32_e32 v101, 16, v221
	v_and_b32_e32 v218, 0xffff0000, v218
	v_and_b32_e32 v219, 0xffff0000, v219
	v_and_b32_e32 v220, 0xffff0000, v220
	v_and_b32_e32 v221, 0xffff0000, v221
	v_mul_f32_e32 v8, v8, v98
	v_mul_f32_e32 v9, v9, v218
	v_mul_f32_e32 v10, v10, v99
	v_mul_f32_e32 v11, v11, v219
	v_mul_f32_e32 v12, v12, v100
	v_mul_f32_e32 v13, v13, v220
	v_mul_f32_e32 v14, v14, v101
	v_mul_f32_e32 v15, v15, v221
	v_lshlrev_b32_e32 v98, 16, v202
	v_lshlrev_b32_e32 v99, 16, v203
	v_lshlrev_b32_e32 v100, 16, v204
	v_lshlrev_b32_e32 v101, 16, v205
	v_and_b32_e32 v202, 0xffff0000, v202
	v_and_b32_e32 v203, 0xffff0000, v203
	v_and_b32_e32 v204, 0xffff0000, v204
	v_and_b32_e32 v205, 0xffff0000, v205
	v_mul_f32_e32 v8, v8, v98
	v_mul_f32_e32 v9, v9, v202
	v_mul_f32_e32 v10, v10, v99
	v_mul_f32_e32 v11, v11, v203
	v_mul_f32_e32 v12, v12, v100
	v_mul_f32_e32 v13, v13, v204
	v_mul_f32_e32 v14, v14, v101
	v_mul_f32_e32 v15, v15, v205
	v_cvt_pk_bf16_f32 v8, v8, v9
	v_cvt_pk_bf16_f32 v9, v10, v11
	v_cvt_pk_bf16_f32 v10, v12, v13
	v_cvt_pk_bf16_f32 v11, v14, v15
	global_store_dwordx4 v236, v[8:11], s[82:83]
	s_add_u32 s82, s82, 0x4000
	s_addc_u32 s83, s83, 0
	s_waitcnt vmcnt(17) lgkmcnt(2)
	v_add_f32_e32 v16, v16, v232
	v_add_f32_e32 v17, v17, v232
	v_add_f32_e32 v18, v18, v232
	v_add_f32_e32 v19, v19, v232
	v_add_f32_e32 v20, v20, v232
	v_add_f32_e32 v21, v21, v232
	v_add_f32_e32 v22, v22, v232
	v_add_f32_e32 v23, v23, v232
	v_lshlrev_b32_e32 v98, 16, v222
	v_lshlrev_b32_e32 v99, 16, v223
	v_lshlrev_b32_e32 v100, 16, v224
	v_lshlrev_b32_e32 v101, 16, v225
	v_and_b32_e32 v222, 0xffff0000, v222
	v_and_b32_e32 v223, 0xffff0000, v223
	v_and_b32_e32 v224, 0xffff0000, v224
	v_and_b32_e32 v225, 0xffff0000, v225
	v_mul_f32_e32 v16, v16, v98
	v_mul_f32_e32 v17, v17, v222
	v_mul_f32_e32 v18, v18, v99
	v_mul_f32_e32 v19, v19, v223
	v_mul_f32_e32 v20, v20, v100
	v_mul_f32_e32 v21, v21, v224
	v_mul_f32_e32 v22, v22, v101
	v_mul_f32_e32 v23, v23, v225
	v_lshlrev_b32_e32 v98, 16, v206
	v_lshlrev_b32_e32 v99, 16, v207
	v_lshlrev_b32_e32 v100, 16, v208
	v_lshlrev_b32_e32 v101, 16, v209
	v_and_b32_e32 v206, 0xffff0000, v206
	v_and_b32_e32 v207, 0xffff0000, v207
	v_and_b32_e32 v208, 0xffff0000, v208
	v_and_b32_e32 v209, 0xffff0000, v209
	v_mul_f32_e32 v16, v16, v98
	v_mul_f32_e32 v17, v17, v206
	v_mul_f32_e32 v18, v18, v99
	v_mul_f32_e32 v19, v19, v207
	v_mul_f32_e32 v20, v20, v100
	v_mul_f32_e32 v21, v21, v208
	v_mul_f32_e32 v22, v22, v101
	v_mul_f32_e32 v23, v23, v209
	v_cvt_pk_bf16_f32 v16, v16, v17
	v_cvt_pk_bf16_f32 v17, v18, v19
	v_cvt_pk_bf16_f32 v18, v20, v21
	v_cvt_pk_bf16_f32 v19, v22, v23
	global_store_dwordx4 v236, v[16:19], s[82:83]
	s_add_u32 s82, s82, 0x4000
	s_addc_u32 s83, s83, 0
	s_waitcnt vmcnt(15) lgkmcnt(0)
	v_add_f32_e32 v24, v24, v233
	v_add_f32_e32 v25, v25, v233
	v_add_f32_e32 v26, v26, v233
	v_add_f32_e32 v27, v27, v233
	v_add_f32_e32 v28, v28, v233
	v_add_f32_e32 v29, v29, v233
	v_add_f32_e32 v30, v30, v233
	v_add_f32_e32 v31, v31, v233
	v_lshlrev_b32_e32 v98, 16, v226
	v_lshlrev_b32_e32 v99, 16, v227
	v_lshlrev_b32_e32 v100, 16, v228
	v_lshlrev_b32_e32 v101, 16, v229
	v_and_b32_e32 v226, 0xffff0000, v226
	v_and_b32_e32 v227, 0xffff0000, v227
	v_and_b32_e32 v228, 0xffff0000, v228
	v_and_b32_e32 v229, 0xffff0000, v229
	v_mul_f32_e32 v24, v24, v98
	v_mul_f32_e32 v25, v25, v226
	v_mul_f32_e32 v26, v26, v99
	v_mul_f32_e32 v27, v27, v227
	v_mul_f32_e32 v28, v28, v100
	v_mul_f32_e32 v29, v29, v228
	v_mul_f32_e32 v30, v30, v101
	v_mul_f32_e32 v31, v31, v229
	v_lshlrev_b32_e32 v98, 16, v210
	v_lshlrev_b32_e32 v99, 16, v211
	v_lshlrev_b32_e32 v100, 16, v212
	v_lshlrev_b32_e32 v101, 16, v213
	v_and_b32_e32 v210, 0xffff0000, v210
	v_and_b32_e32 v211, 0xffff0000, v211
	v_and_b32_e32 v212, 0xffff0000, v212
	v_and_b32_e32 v213, 0xffff0000, v213
	v_mul_f32_e32 v24, v24, v98
	v_mul_f32_e32 v25, v25, v210
	v_mul_f32_e32 v26, v26, v99
	v_mul_f32_e32 v27, v27, v211
	v_mul_f32_e32 v28, v28, v100
	v_mul_f32_e32 v29, v29, v212
	v_mul_f32_e32 v30, v30, v101
	v_mul_f32_e32 v31, v31, v213
	v_cvt_pk_bf16_f32 v24, v24, v25
	v_cvt_pk_bf16_f32 v25, v26, v27
	v_cvt_pk_bf16_f32 v26, v28, v29
	v_cvt_pk_bf16_f32 v27, v30, v31
	global_store_dwordx4 v236, v[24:27], s[82:83]
	s_add_u32 s82, s82, 0x4000
	s_addc_u32 s83, s83, 0
	ds_write_b32 v239, v32 offset:0
	ds_write_b32 v239, v33 offset:512
	ds_write_b32 v239, v34 offset:1024
	ds_write_b32 v239, v35 offset:1536
	ds_write_b32 v239, v36 offset:64
	ds_write_b32 v239, v37 offset:576
	ds_write_b32 v239, v38 offset:1088
	ds_write_b32 v239, v39 offset:1600
	ds_write_b32 v239, v40 offset:128
	ds_write_b32 v239, v41 offset:640
	ds_write_b32 v239, v42 offset:1152
	ds_write_b32 v239, v43 offset:1664
	ds_write_b32 v239, v44 offset:192
	ds_write_b32 v239, v45 offset:704
	ds_write_b32 v239, v46 offset:1216
	ds_write_b32 v239, v47 offset:1728
	ds_write_b32 v239, v48 offset:256
	ds_write_b32 v239, v49 offset:768
	ds_write_b32 v239, v50 offset:1280
	ds_write_b32 v239, v51 offset:1792
	ds_write_b32 v239, v52 offset:320
	ds_write_b32 v239, v53 offset:832
	ds_write_b32 v239, v54 offset:1344
	ds_write_b32 v239, v55 offset:1856
	ds_write_b32 v240, v56 offset:0
	ds_write_b32 v240, v57 offset:512
	ds_write_b32 v240, v58 offset:1024
	ds_write_b32 v240, v59 offset:1536
	ds_write_b32 v241, v60 offset:0
	ds_write_b32 v241, v61 offset:512
	ds_write_b32 v241, v62 offset:1024
	ds_write_b32 v241, v63 offset:1536
	s_waitcnt lgkmcnt(0)
	ds_read_b128 v[32:35], v242
	ds_read_b128 v[36:39], v242 offset:16
	ds_read_b128 v[40:43], v243
	ds_read_b128 v[44:47], v243 offset:16
	ds_read_b128 v[48:51], v244
	ds_read_b128 v[52:55], v244 offset:16
	ds_read_b128 v[56:59], v245
	ds_read_b128 v[60:63], v245 offset:16
	s_waitcnt vmcnt(13) lgkmcnt(6)
	v_add_f32_e32 v32, v32, v94
	v_add_f32_e32 v33, v33, v94
	v_add_f32_e32 v34, v34, v94
	v_add_f32_e32 v35, v35, v94
	v_add_f32_e32 v36, v36, v94
	v_add_f32_e32 v37, v37, v94
	v_add_f32_e32 v38, v38, v94
	v_add_f32_e32 v39, v39, v94
	v_lshlrev_b32_e32 v98, 16, v190
	v_lshlrev_b32_e32 v99, 16, v191
	v_lshlrev_b32_e32 v100, 16, v192
	v_lshlrev_b32_e32 v101, 16, v193
	v_and_b32_e32 v190, 0xffff0000, v190
	v_and_b32_e32 v191, 0xffff0000, v191
	v_and_b32_e32 v192, 0xffff0000, v192
	v_and_b32_e32 v193, 0xffff0000, v193
	v_mul_f32_e32 v32, v32, v98
	v_mul_f32_e32 v33, v33, v190
	v_mul_f32_e32 v34, v34, v99
	v_mul_f32_e32 v35, v35, v191
	v_mul_f32_e32 v36, v36, v100
	v_mul_f32_e32 v37, v37, v192
	v_mul_f32_e32 v38, v38, v101
	v_mul_f32_e32 v39, v39, v193
	v_lshlrev_b32_e32 v98, 16, v174
	v_lshlrev_b32_e32 v99, 16, v175
	v_lshlrev_b32_e32 v100, 16, v176
	v_lshlrev_b32_e32 v101, 16, v177
	v_and_b32_e32 v174, 0xffff0000, v174
	v_and_b32_e32 v175, 0xffff0000, v175
	v_and_b32_e32 v176, 0xffff0000, v176
	v_and_b32_e32 v177, 0xffff0000, v177
	v_mul_f32_e32 v32, v32, v98
	v_mul_f32_e32 v33, v33, v174
	v_mul_f32_e32 v34, v34, v99
	v_mul_f32_e32 v35, v35, v175
	v_mul_f32_e32 v36, v36, v100
	v_mul_f32_e32 v37, v37, v176
	v_mul_f32_e32 v38, v38, v101
	v_mul_f32_e32 v39, v39, v177
	v_cvt_pk_bf16_f32 v32, v32, v33
	v_cvt_pk_bf16_f32 v33, v34, v35
	v_cvt_pk_bf16_f32 v34, v36, v37
	v_cvt_pk_bf16_f32 v35, v38, v39
	global_store_dwordx4 v236, v[32:35], s[82:83]
	s_add_u32 s82, s82, 0x4000
	s_addc_u32 s83, s83, 0
	s_waitcnt vmcnt(11) lgkmcnt(4)
	v_add_f32_e32 v40, v40, v95
	v_add_f32_e32 v41, v41, v95
	v_add_f32_e32 v42, v42, v95
	v_add_f32_e32 v43, v43, v95
	v_add_f32_e32 v44, v44, v95
	v_add_f32_e32 v45, v45, v95
	v_add_f32_e32 v46, v46, v95
	v_add_f32_e32 v47, v47, v95
	v_lshlrev_b32_e32 v98, 16, v194
	v_lshlrev_b32_e32 v99, 16, v195
	v_lshlrev_b32_e32 v100, 16, v196
	v_lshlrev_b32_e32 v101, 16, v197
	v_and_b32_e32 v194, 0xffff0000, v194
	v_and_b32_e32 v195, 0xffff0000, v195
	v_and_b32_e32 v196, 0xffff0000, v196
	v_and_b32_e32 v197, 0xffff0000, v197
	v_mul_f32_e32 v40, v40, v98
	v_mul_f32_e32 v41, v41, v194
	v_mul_f32_e32 v42, v42, v99
	v_mul_f32_e32 v43, v43, v195
	v_mul_f32_e32 v44, v44, v100
	v_mul_f32_e32 v45, v45, v196
	v_mul_f32_e32 v46, v46, v101
	v_mul_f32_e32 v47, v47, v197
	v_lshlrev_b32_e32 v98, 16, v178
	v_lshlrev_b32_e32 v99, 16, v179
	v_lshlrev_b32_e32 v100, 16, v180
	v_lshlrev_b32_e32 v101, 16, v181
	v_and_b32_e32 v178, 0xffff0000, v178
	v_and_b32_e32 v179, 0xffff0000, v179
	v_and_b32_e32 v180, 0xffff0000, v180
	v_and_b32_e32 v181, 0xffff0000, v181
	v_mul_f32_e32 v40, v40, v98
	v_mul_f32_e32 v41, v41, v178
	v_mul_f32_e32 v42, v42, v99
	v_mul_f32_e32 v43, v43, v179
	v_mul_f32_e32 v44, v44, v100
	v_mul_f32_e32 v45, v45, v180
	v_mul_f32_e32 v46, v46, v101
	v_mul_f32_e32 v47, v47, v181
	v_cvt_pk_bf16_f32 v40, v40, v41
	v_cvt_pk_bf16_f32 v41, v42, v43
	v_cvt_pk_bf16_f32 v42, v44, v45
	v_cvt_pk_bf16_f32 v43, v46, v47
	global_store_dwordx4 v236, v[40:43], s[82:83]
	s_add_u32 s82, s82, 0x4000
	s_addc_u32 s83, s83, 0
	s_waitcnt vmcnt(9) lgkmcnt(2)
	v_add_f32_e32 v48, v48, v96
	v_add_f32_e32 v49, v49, v96
	v_add_f32_e32 v50, v50, v96
	v_add_f32_e32 v51, v51, v96
	v_add_f32_e32 v52, v52, v96
	v_add_f32_e32 v53, v53, v96
	v_add_f32_e32 v54, v54, v96
	v_add_f32_e32 v55, v55, v96
	v_lshlrev_b32_e32 v98, 16, v64
	v_lshlrev_b32_e32 v99, 16, v65
	v_lshlrev_b32_e32 v100, 16, v66
	v_lshlrev_b32_e32 v101, 16, v67
	v_and_b32_e32 v64, 0xffff0000, v64
	v_and_b32_e32 v65, 0xffff0000, v65
	v_and_b32_e32 v66, 0xffff0000, v66
	v_and_b32_e32 v67, 0xffff0000, v67
	v_mul_f32_e32 v48, v48, v98
	v_mul_f32_e32 v49, v49, v64
	v_mul_f32_e32 v50, v50, v99
	v_mul_f32_e32 v51, v51, v65
	v_mul_f32_e32 v52, v52, v100
	v_mul_f32_e32 v53, v53, v66
	v_mul_f32_e32 v54, v54, v101
	v_mul_f32_e32 v55, v55, v67
	v_lshlrev_b32_e32 v98, 16, v182
	v_lshlrev_b32_e32 v99, 16, v183
	v_lshlrev_b32_e32 v100, 16, v184
	v_lshlrev_b32_e32 v101, 16, v185
	v_and_b32_e32 v182, 0xffff0000, v182
	v_and_b32_e32 v183, 0xffff0000, v183
	v_and_b32_e32 v184, 0xffff0000, v184
	v_and_b32_e32 v185, 0xffff0000, v185
	v_mul_f32_e32 v48, v48, v98
	v_mul_f32_e32 v49, v49, v182
	v_mul_f32_e32 v50, v50, v99
	v_mul_f32_e32 v51, v51, v183
	v_mul_f32_e32 v52, v52, v100
	v_mul_f32_e32 v53, v53, v184
	v_mul_f32_e32 v54, v54, v101
	v_mul_f32_e32 v55, v55, v185
	v_cvt_pk_bf16_f32 v48, v48, v49
	v_cvt_pk_bf16_f32 v49, v50, v51
	v_cvt_pk_bf16_f32 v50, v52, v53
	v_cvt_pk_bf16_f32 v51, v54, v55
	global_store_dwordx4 v236, v[48:51], s[82:83]
	s_add_u32 s82, s82, 0x4000
	s_addc_u32 s83, s83, 0
	s_waitcnt vmcnt(7) lgkmcnt(0)
	v_add_f32_e32 v56, v56, v97
	v_add_f32_e32 v57, v57, v97
	v_add_f32_e32 v58, v58, v97
	v_add_f32_e32 v59, v59, v97
	v_add_f32_e32 v60, v60, v97
	v_add_f32_e32 v61, v61, v97
	v_add_f32_e32 v62, v62, v97
	v_add_f32_e32 v63, v63, v97
	v_lshlrev_b32_e32 v98, 16, v68
	v_lshlrev_b32_e32 v99, 16, v69
	v_lshlrev_b32_e32 v100, 16, v70
	v_lshlrev_b32_e32 v101, 16, v71
	v_and_b32_e32 v68, 0xffff0000, v68
	v_and_b32_e32 v69, 0xffff0000, v69
	v_and_b32_e32 v70, 0xffff0000, v70
	v_and_b32_e32 v71, 0xffff0000, v71
	v_mul_f32_e32 v56, v56, v98
	v_mul_f32_e32 v57, v57, v68
	v_mul_f32_e32 v58, v58, v99
	v_mul_f32_e32 v59, v59, v69
	v_mul_f32_e32 v60, v60, v100
	v_mul_f32_e32 v61, v61, v70
	v_mul_f32_e32 v62, v62, v101
	v_mul_f32_e32 v63, v63, v71
	v_lshlrev_b32_e32 v98, 16, v186
	v_lshlrev_b32_e32 v99, 16, v187
	v_lshlrev_b32_e32 v100, 16, v188
	v_lshlrev_b32_e32 v101, 16, v189
	v_and_b32_e32 v186, 0xffff0000, v186
	v_and_b32_e32 v187, 0xffff0000, v187
	v_and_b32_e32 v188, 0xffff0000, v188
	v_and_b32_e32 v189, 0xffff0000, v189
	v_mul_f32_e32 v56, v56, v98
	v_mul_f32_e32 v57, v57, v186
	v_mul_f32_e32 v58, v58, v99
	v_mul_f32_e32 v59, v59, v187
	v_mul_f32_e32 v60, v60, v100
	v_mul_f32_e32 v61, v61, v188
	v_mul_f32_e32 v62, v62, v101
	v_mul_f32_e32 v63, v63, v189
	v_cvt_pk_bf16_f32 v56, v56, v57
	v_cvt_pk_bf16_f32 v57, v58, v59
	v_cvt_pk_bf16_f32 v58, v60, v61
	v_cvt_pk_bf16_f32 v59, v62, v63
	global_store_dwordx4 v236, v[56:59], s[82:83]
	s_add_u32 s82, s82, 0x4000
	s_addc_u32 s83, s83, 0
	s_branch .LBB0_251
.LBB0_255:
	s_and_b32 s8, s33, 63
	s_lshl_b32 s90, s8, 6
	s_andn2_b32 s10, 63, s88
	s_ashr_i32 s8, s88, 9
	s_lshl_b32 s80, s10, 6
	s_ashr_i32 s9, s8, 31
	s_lshl_b64 s[82:83], s[8:9], 12
	v_add_u32_e32 v60, s80, v115
	v_mov_b32_e32 v61, v72
	v_or_b32_e32 v16, s80, v128
	v_lshl_add_u64 v[0:1], s[82:83], 0, v[60:61]
	v_mov_b32_e32 v17, s83
	v_or_b32_e32 v16, s82, v16
	s_bfe_u32 s11, s88, 0x30006
	v_lshlrev_b64 v[0:1], 11, v[0:1]
	v_lshlrev_b64 v[16:17], 11, v[16:17]
	v_lshl_add_u64 v[0:1], s[30:31], 0, v[0:1]
	s_lshl_b32 s28, s11, 8
	v_lshl_add_u64 v[16:17], s[34:35], 0, v[16:17]
	v_lshl_add_u64 v[0:1], v[0:1], 0, s[28:29]
	v_mov_b32_e32 v85, v72
	v_lshl_add_u64 v[16:17], v[16:17], 0, s[28:29]
	v_mov_b32_e32 v87, v72
	v_readfirstlane_b32 s9, v129
	v_lshl_add_u64 v[12:13], v[0:1], 0, v[84:85]
	v_lshl_add_u64 v[16:17], v[16:17], 0, v[86:87]
	s_mov_b32 m0, s9
	v_readfirstlane_b32 s9, v141
	global_load_dwordx4 v[0:3], v[12:13], off
	global_load_dwordx4 v[4:7], v[12:13], off offset:64
	global_load_dwordx4 v[8:11], v[12:13], off offset:128
	s_nop 0
	global_load_dwordx4 v[12:15], v[12:13], off offset:192
	s_barrier
	global_load_lds_dwordx4 v[16:17], off
	v_lshl_add_u64 v[18:19], v[16:17], 0, s[66:67]
	s_mov_b32 m0, s9
	v_readfirstlane_b32 s9, v142
	s_lshl_b32 s8, s8, 3
	global_load_lds_dwordx4 v[18:19], off
	v_lshl_add_u64 v[18:19], v[16:17], 0, s[70:71]
	s_mov_b32 m0, s9
	v_readfirstlane_b32 s9, v143
	s_or_b32 s8, s11, s8
	global_load_lds_dwordx4 v[18:19], off
	s_mov_b32 m0, s9
	s_ashr_i32 s9, s8, 31
	s_lshl_b32 s89, s11, 7
	s_lshl_b64 s[8:9], s[8:9], 20
	v_readlane_b32 s11, v247, 3
	s_add_u32 s8, s11, s8
	v_readlane_b32 s11, v247, 4
	s_addc_u32 s9, s11, s9
	s_lshl_b32 s10, s10, 7
	s_add_u32 s10, s8, s10
	v_lshl_add_u64 v[16:17], v[16:17], 0, s[72:73]
	s_addc_u32 s11, s9, 0
	v_mov_b32_e32 v89, v72
	global_load_lds_dwordx4 v[16:17], off
	v_lshl_add_u64 v[16:17], s[10:11], 0, v[88:89]
	v_mov_b32_e32 v91, v72
	v_readfirstlane_b32 s10, v144
	v_lshl_add_u64 v[16:17], v[16:17], 0, v[90:91]
	s_mov_b32 m0, s10
	v_readfirstlane_b32 s10, v145
	global_load_lds_dwordx4 v[16:17], off
	v_lshl_add_u64 v[18:19], v[16:17], 0, s[74:75]
	s_mov_b32 m0, s10
	v_readfirstlane_b32 s10, v146
	global_load_lds_dwordx4 v[18:19], off
	v_lshl_add_u64 v[18:19], v[16:17], 0, s[76:77]
	s_mov_b32 m0, s10
	v_readfirstlane_b32 s10, v147
	global_load_lds_dwordx4 v[18:19], off
	v_lshl_add_u64 v[16:17], v[16:17], 0, s[78:79]
	s_mov_b32 m0, s10
	v_mov_b32_e32 v69, 0
	global_load_lds_dwordx4 v[16:17], off
	v_lshl_add_u64 v[16:17], s[8:9], 0, v[88:89]
	v_lshl_add_u64 v[64:65], v[16:17], 0, v[90:91]
	v_and_b32_e32 v17, 64, v172
	v_xor_b32_e32 v16, 16, v172
	v_add_u32_e32 v17, 64, v17
	v_cmp_lt_i32_e32 vcc, v16, v17
	s_waitcnt vmcnt(0)
	v_readfirstlane_b32 s101, v100
	s_mov_b32 s81, s29
	v_lshl_add_u64 v[62:63], v[82:83], 0, s[28:29]
	v_cndmask_b32_e32 v16, v172, v16, vcc
	v_lshlrev_b32_e32 v85, 2, v16
	v_xor_b32_e32 v16, 32, v172
	v_cmp_lt_i32_e32 vcc, v16, v17
	v_mov_b32_e32 v67, s83
	v_or_b32_e32 v66, s82, v128
	v_cndmask_b32_e32 v16, v172, v16, vcc
	v_lshlrev_b32_e32 v87, 2, v16
	v_xor_b32_e32 v16, 1, v172
	v_cmp_lt_i32_e32 vcc, v16, v17
	s_mov_b32 s91, 0
	v_mov_b32_e32 v61, v60
	v_cndmask_b32_e32 v16, v172, v16, vcc
	v_lshlrev_b32_e32 v89, 2, v16
	v_xor_b32_e32 v16, 2, v172
	v_cmp_lt_i32_e32 vcc, v16, v17
	v_mov_b32_e32 v18, v69
	v_mov_b32_e32 v19, v69
	v_cndmask_b32_e32 v16, v172, v16, vcc
	v_lshlrev_b32_e32 v91, 2, v16
	v_xor_b32_e32 v16, 4, v172
	v_cmp_lt_i32_e32 vcc, v16, v17
	v_mov_b32_e32 v20, v69
	v_mov_b32_e32 v21, v69
	v_cndmask_b32_e32 v16, v172, v16, vcc
	v_lshlrev_b32_e32 v93, 2, v16
	v_xor_b32_e32 v16, 8, v172
	v_cmp_lt_i32_e32 vcc, v16, v17
	v_mov_b32_e32 v17, v69
	v_mov_b32_e32 v22, v69
	v_cndmask_b32_e32 v16, v172, v16, vcc
	v_lshlrev_b32_e32 v173, 2, v16
	v_mov_b32_e32 v16, v69
	v_mov_b32_e32 v23, v69
	v_mov_b32_e32 v24, v69
	v_mov_b32_e32 v25, v69
	v_mov_b32_e32 v26, v69
	v_mov_b32_e32 v27, v69
	v_mov_b32_e32 v32, v69
	v_mov_b32_e32 v33, v69
	v_mov_b32_e32 v34, v69
	v_mov_b32_e32 v35, v69
	v_mov_b32_e32 v28, v69
	v_mov_b32_e32 v29, v69
	v_mov_b32_e32 v30, v69
	v_mov_b32_e32 v31, v69
	v_mov_b32_e32 v36, v69
	v_mov_b32_e32 v37, v69
	v_mov_b32_e32 v38, v69
	v_mov_b32_e32 v39, v69
	v_mov_b32_e32 v40, v69
	v_mov_b32_e32 v41, v69
	v_mov_b32_e32 v42, v69
	v_mov_b32_e32 v43, v69
	v_mov_b32_e32 v44, v69
	v_mov_b32_e32 v45, v69
	v_mov_b32_e32 v46, v69
	v_mov_b32_e32 v47, v69
	s_waitcnt vmcnt(0) lgkmcnt(0)
	s_barrier
	s_branch .LBB0_257
